# work-queue dequeue for the next unit issued at the start of the attention phase, loop head only publishes it
# speedup vs baseline: 1.0351x; 1.0042x over previous
; #define LAS __attribute__((address_space(3)))
; #define GAS __attribute__((address_space(1)))
; __global__ void __launch_bounds__(512, 2) mk_fwd(Args a) {
;     ...
;     {
;         Args a5{}; a5.ws = ws;
;         const int nml = (G > 64) ? 64 : (G > 1 ? G / 2 : 0);
;         if (vb < nml) { for (int u = vb; u < 64 * DUP_ML; u += nml) mlstm_unit(a5, lds, (u >> 2) & 15, u & 3, tid, wave, lane); }
;         {
;             LAS unsigned long long* maskl = (LAS unsigned long long*)(lds + 135168);
;             volatile LAS int* slot = (volatile LAS int*)(lds + 131072 + 128);
;             const int x = vb & 7; GAS unsigned* qc = (GAS unsigned*)(ws + WS_BAR) + 64 * (1 + x);
;             for (;;) {
;                 if (tid == 0) *slot = (int)__hip_atomic_fetch_add(qc, 1u, __ATOMIC_RELAXED, __HIP_MEMORY_SCOPE_AGENT);
;                 __syncthreads();
;                 const int j = __builtin_amdgcn_readfirstlane(*slot);
;                 if (j >= 128) break;
;                 const int bb = 2 * x + (j & 1), qb = 63 - (j >> 1);
.LBB0_1072:
	s_and_b32 s2, s89, 7
	s_lshl_b32 s0, s2, 8
	s_add_u32 s0, s80, s0
	s_addc_u32 s1, s81, 0
	s_add_u32 s0, s0, 0xa08000
	s_addc_u32 s1, s1, 0
	v_writelane_b32 v254, s0, 20
	v_mbcnt_hi_u32_b32 v253, -1, v225
	v_and_b32_e32 v0, 64, v253
	v_writelane_b32 v254, s1, 21
	v_writelane_b32 v254, s2, 22
	s_lshl_b32 s0, s2, 1
	v_writelane_b32 v254, s0, 23
	s_add_u32 s0, s80, 0x8400000
	s_addc_u32 s1, s81, 0
	v_writelane_b32 v254, s0, 24
	s_mov_b32 s19, 0
	v_mov_b32_e32 v4, 0
	v_writelane_b32 v254, s1, 25
	s_add_u32 s0, s80, 0x1c400000
	s_addc_u32 s1, s81, 0
	s_add_u32 s8, s80, 0x1b400000
	v_writelane_b32 v254, s0, 26
	s_addc_u32 s9, s81, 0
	s_brev_b32 s89, 1
	v_writelane_b32 v254, s1, 27
	s_add_u32 s0, s80, 0x1bc00000
	s_addc_u32 s1, s81, 0
	v_writelane_b32 v254, s0, 28
	v_mov_b32_e32 v185, 0x260
	v_xor_b32_e32 v227, 16, v253
	v_writelane_b32 v254, s1, 29
	v_add_u32_e32 v226, 64, v0
	v_readlane_b32 s3, v254, 4
	s_lshl_b32 s2, s3, 7
	s_add_u32 s0, s80, 0xa10000
	s_addc_u32 s1, s81, 0
	v_writelane_b32 v254, s0, 30
	s_and_b32 s4, s86, 0xffffffc0
	s_ashr_i32 s5, s4, 31
	v_writelane_b32 v254, s1, 31
	s_mov_b32 s0, s4
	v_writelane_b32 v254, s0, 32
	s_nop 1
	v_writelane_b32 v254, s1, 33
	s_lshl_b64 s[0:1], s[4:5], 1
	s_add_u32 s0, s80, s0
	s_addc_u32 s1, s81, s1
	s_add_u32 s0, s0, 0x17400000
	s_addc_u32 s1, s1, 0
	v_writelane_b32 v254, s0, 34
	s_nop 1
	v_writelane_b32 v254, s1, 35
	s_lshl_b32 s0, s3, 6
	s_add_i32 s0, s0, 0
	v_writelane_b32 v254, s0, 36
	s_add_i32 s0, 0, 0x20080
	v_writelane_b32 v254, s0, 37
	v_mov_b32_e32 v183, s0
	s_lshl_b32 s0, s2, 1
	v_writelane_b32 v254, s0, 38
	s_nop 1
	v_writelane_b32 v254, s1, 39
	s_add_i32 s0, 0, 0x21008
	v_writelane_b32 v254, s0, 40
	v_writelane_b32 v254, s8, 41
	s_nop 1
	v_writelane_b32 v254, s9, 42
	s_mov_b64 s[20:21], exec
	v_readlane_b32 s22, v254, 2
	v_readlane_b32 s23, v254, 3
	s_and_b64 exec, s[20:21], s[22:23]
	s_cbranch_execz .Ldq_prime_skip
	v_readlane_b32 s22, v254, 20
	v_readlane_b32 s23, v254, 21
	v_mov_b32_e32 v205, 1
	s_nop 4
	global_atomic_add v205, v4, v205, s[22:23] offset:256 sc0
	s_waitcnt vmcnt(0)
.Ldq_prime_skip:
	s_mov_b64 exec, s[20:21]
	s_branch .LBB0_1075

; __global__ void __launch_bounds__(512, 2) mk_fwd(Args a) {
;     ...
;             for (;;) {
;                 if (tid == 0) *slot = (int)__hip_atomic_fetch_add(qc, 1u, __ATOMIC_RELAXED, __HIP_MEMORY_SCOPE_AGENT);
;                 __syncthreads();
;                 const int j = __builtin_amdgcn_readfirstlane(*slot);
.LBB0_1075:
	s_mov_b64 s[0:1], exec
	v_readlane_b32 s2, v254, 2
	v_readlane_b32 s3, v254, 3
	s_and_b64 s[2:3], s[0:1], s[2:3]
	s_mov_b64 exec, s[2:3]
	s_cbranch_execz .LBB0_1079
	v_readlane_b32 s2, v254, 37
	s_nop 1
	v_mov_b32_e32 v1, s2
	ds_write_b32 v1, v205

; #define GAS __attribute__((address_space(1)))
; __device__ __forceinline__ void dsa_unit32(const Args& a, LAS unsigned char* lds, const LAS unsigned long long* maskl, int b, int qb, int tid, int wave, int lane) {
;     ...
;     for (int ks = 0; ks < 8; ++ks) { const u32x4 w = __builtin_nontemporal_load((const GAS u32x4*)(z + (rowb + t0 + l31) * ZW + ZDQ + h * 128 + 16 * ks + 8 * hi)); qf[ks] = __builtin_bit_cast(bf16x8, w);
; #pragma unroll
;         for (int i = 0; i < 4; ++i) { const float x0 = bflo(w[i]), x1 = bfhi(w[i]); qs += x0 * x0 + x1 * x1; } }
;     qs += __shfl_xor(qs, 32);
;     const float negB = -1.01f * 11.313708498984761f * sqrtf(qs);
; __global__ void __launch_bounds__(512, 2) mk_fwd(Args a) {
;     ...
;                 if (tid == 0) *slot = (int)__hip_atomic_fetch_add(qc, 1u, __ATOMIC_RELAXED, __HIP_MEMORY_SCOPE_AGENT);
.LBB0_1298:
	v_readlane_b32 s17, v254, 4
	v_readlane_b32 s0, v254, 43
	v_mov_b32_e32 v15, v252
	s_lshl_b32 s4, s0, 5
	v_readlane_b32 s0, v254, 46
	s_add_i32 s0, s0, s4
	v_and_b32_e32 v5, 31, v15
	v_or_b32_e32 v178, s0, v5
	v_readlane_b32 s0, v254, 24
	v_readlane_b32 s1, v254, 25
	v_bfe_u32 v14, v15, 5, 1
	v_lshlrev_b32_e32 v180, 4, v14
	s_movk_i32 s0, 0x1e00
	v_readlane_b32 s0, v254, 38
	v_readlane_b32 s1, v254, 39
	s_mov_b32 s1, s19
	v_mov_b32_e32 v181, v4
	s_mov_b32 s2, s0
	s_mov_b64 s[0:1], 0x1000
	v_writelane_b32 v254, s2, 38
	s_movk_i32 s0, 0xf000
	s_waitcnt vmcnt(0)
	s_mov_b64 s[20:21], exec
	v_readlane_b32 s22, v254, 2
	v_readlane_b32 s23, v254, 3
	s_and_b64 exec, s[20:21], s[22:23]
	s_cbranch_execz .Ldq_pf_skip
	v_readlane_b32 s22, v254, 20
	v_readlane_b32 s23, v254, 21
	v_mov_b32_e32 v205, 1
	s_nop 4
	global_atomic_add v205, v4, v205, s[22:23] offset:256 sc0
.Ldq_pf_skip:
	s_mov_b64 exec, s[20:21]
	v_and_b32_e32 v7, 0xffff0000, v0
	v_and_b32_e32 v33, 0xffff0000, v126
	v_and_b32_e32 v35, 0xffff0000, v127
	v_lshlrev_b32_e32 v32, 16, v126
	v_lshlrev_b32_e32 v34, 16, v127
	v_and_b32_e32 v37, 0xffff0000, v128
	v_mul_f32_e32 v33, v33, v33
	v_mul_f32_e32 v35, v35, v35
	v_lshlrev_b32_e32 v6, 16, v0
	v_lshlrev_b32_e32 v36, 16, v128
	v_and_b32_e32 v39, 0xffff0000, v129
	v_mul_f32_e32 v7, v7, v7
	v_mul_f32_e32 v37, v37, v37
	v_fmac_f32_e32 v33, v32, v32
	v_fmac_f32_e32 v35, v34, v34
	v_lshlrev_b32_e32 v38, 16, v129
	v_mul_f32_e32 v39, v39, v39
	v_fmac_f32_e32 v7, v6, v6
	v_fmac_f32_e32 v37, v36, v36
	v_add_f32_e32 v6, v33, v35
	v_and_b32_e32 v9, 0xffff0000, v1
	v_fmac_f32_e32 v39, v38, v38
	v_add_f32_e32 v6, v37, v6
	v_lshlrev_b32_e32 v8, 16, v1
	v_and_b32_e32 v11, 0xffff0000, v2
	v_mul_f32_e32 v9, v9, v9
	v_add_f32_e32 v6, v39, v6
	v_lshlrev_b32_e32 v10, 16, v2
	v_and_b32_e32 v13, 0xffff0000, v3
	v_mul_f32_e32 v11, v11, v11
	v_fmac_f32_e32 v9, v8, v8
	v_add_f32_e32 v6, v7, v6
	v_lshlrev_b32_e32 v12, 16, v3
	v_and_b32_e32 v17, 0xffff0000, v118
	v_mul_f32_e32 v13, v13, v13
	v_fmac_f32_e32 v11, v10, v10
	v_add_f32_e32 v6, v9, v6
	v_lshlrev_b32_e32 v16, 16, v118
	v_and_b32_e32 v19, 0xffff0000, v119
	v_mul_f32_e32 v17, v17, v17
	v_fmac_f32_e32 v13, v12, v12
	v_add_f32_e32 v6, v11, v6
	v_lshlrev_b32_e32 v18, 16, v119
	v_and_b32_e32 v21, 0xffff0000, v120
	v_mul_f32_e32 v19, v19, v19
	v_fmac_f32_e32 v17, v16, v16
	v_add_f32_e32 v6, v13, v6
	v_lshlrev_b32_e32 v20, 16, v120
	v_and_b32_e32 v23, 0xffff0000, v121
	v_mul_f32_e32 v21, v21, v21
	v_fmac_f32_e32 v19, v18, v18
	v_add_f32_e32 v6, v17, v6
	v_lshlrev_b32_e32 v22, 16, v121
	v_and_b32_e32 v25, 0xffff0000, v122
	v_mul_f32_e32 v23, v23, v23
	v_fmac_f32_e32 v21, v20, v20
	v_add_f32_e32 v6, v19, v6
	v_lshlrev_b32_e32 v24, 16, v122
	v_and_b32_e32 v27, 0xffff0000, v123
	v_mul_f32_e32 v25, v25, v25
	v_fmac_f32_e32 v23, v22, v22
	v_add_f32_e32 v6, v21, v6
	v_lshlrev_b32_e32 v26, 16, v123
	v_and_b32_e32 v29, 0xffff0000, v124
	v_mul_f32_e32 v27, v27, v27
	v_fmac_f32_e32 v25, v24, v24
	v_add_f32_e32 v6, v23, v6
	v_lshlrev_b32_e32 v28, 16, v124
	v_and_b32_e32 v31, 0xffff0000, v125
	v_mul_f32_e32 v29, v29, v29
	v_fmac_f32_e32 v27, v26, v26
	v_add_f32_e32 v6, v25, v6
	v_lshlrev_b32_e32 v30, 16, v125
	v_mul_f32_e32 v31, v31, v31
	v_fmac_f32_e32 v29, v28, v28
	v_add_f32_e32 v6, v27, v6
	v_and_b32_e32 v8, 0xffff0000, v130
	v_add_f32_e32 v6, v29, v6
	v_fmac_f32_e32 v31, v30, v30
	v_lshlrev_b32_e32 v7, 16, v130
	v_mul_f32_e32 v8, v8, v8
	v_add_f32_e32 v6, v31, v6
	v_fmac_f32_e32 v8, v7, v7
	v_add_f32_e32 v6, v8, v6
	v_and_b32_e32 v8, 0xffff0000, v131
	v_lshlrev_b32_e32 v7, 16, v131
	v_mul_f32_e32 v8, v8, v8
	v_fmac_f32_e32 v8, v7, v7
	v_add_f32_e32 v7, v8, v6
	v_lshlrev_b32_e32 v6, 4, v15
	v_writelane_b32 v254, s3, 39
	v_lshlrev_b32_e32 v10, 9, v15
	v_and_b32_e32 v16, 0x70, v6
	v_and_or_b32 v10, v10, s0, v16
	v_readlane_b32 s0, v254, 45
	s_lshl_b32 s18, s0, 19
	v_readlane_b32 s8, v254, 41
	v_readlane_b32 s9, v254, 42
	s_add_u32 s0, s8, s18
	s_addc_u32 s1, s9, 0
	v_readlane_b32 s2, v254, 28
	v_readlane_b32 s3, v254, 29
	s_add_u32 s2, s2, s18
	v_add_u32_e32 v8, 0x2000, v6
	v_add_u32_e32 v12, 0x40000, v10
	s_addc_u32 s3, s3, 0
	v_and_b32_e32 v11, 0xffff0000, v132
	v_lshlrev_b32_e32 v9, 16, v132
	v_mul_f32_e32 v11, v11, v11
	v_fmac_f32_e32 v11, v9, v9
	v_add_f32_e32 v7, v11, v7
	v_and_b32_e32 v11, 0xffff0000, v133
	v_lshlrev_b32_e32 v9, 16, v133
	v_mul_f32_e32 v11, v11, v11
	v_fmac_f32_e32 v11, v9, v9
	v_add_f32_e32 v7, v11, v7
	v_and_b32_e32 v11, 0xffff0000, v134
	v_lshlrev_b32_e32 v9, 16, v134
	v_mul_f32_e32 v11, v11, v11
	v_fmac_f32_e32 v11, v9, v9
	v_add_f32_e32 v7, v11, v7
	v_and_b32_e32 v11, 0xffff0000, v135
	v_lshlrev_b32_e32 v9, 16, v135
	v_mul_f32_e32 v11, v11, v11
	v_fmac_f32_e32 v11, v9, v9
	v_add_f32_e32 v7, v11, v7
	v_and_b32_e32 v11, 0xffff0000, v136
	v_lshlrev_b32_e32 v9, 16, v136
	v_mul_f32_e32 v11, v11, v11
	v_fmac_f32_e32 v11, v9, v9
	v_add_f32_e32 v7, v11, v7
	v_and_b32_e32 v11, 0xffff0000, v137
	v_lshlrev_b32_e32 v9, 16, v137
	v_mul_f32_e32 v11, v11, v11
	v_fmac_f32_e32 v11, v9, v9
	v_add_f32_e32 v7, v11, v7
	v_and_b32_e32 v11, 0xffff0000, v138
	v_lshlrev_b32_e32 v9, 16, v138
	v_mul_f32_e32 v11, v11, v11
	v_fmac_f32_e32 v11, v9, v9
	v_add_f32_e32 v7, v11, v7
	v_and_b32_e32 v11, 0xffff0000, v139
	v_lshlrev_b32_e32 v9, 16, v139
	v_mul_f32_e32 v11, v11, v11
	v_fmac_f32_e32 v11, v9, v9
	v_add_f32_e32 v7, v11, v7
	v_and_b32_e32 v11, 0xffff0000, v140
	v_lshlrev_b32_e32 v9, 16, v140
	v_mul_f32_e32 v11, v11, v11
	v_fmac_f32_e32 v11, v9, v9
	v_add_f32_e32 v7, v11, v7
	v_and_b32_e32 v11, 0xffff0000, v141
	v_lshlrev_b32_e32 v9, 16, v141
	v_mul_f32_e32 v11, v11, v11
	v_fmac_f32_e32 v11, v9, v9
	v_add_f32_e32 v7, v11, v7
	v_and_b32_e32 v11, 0xffff0000, v142
	v_lshlrev_b32_e32 v9, 16, v142
	v_mul_f32_e32 v11, v11, v11
	v_fmac_f32_e32 v11, v9, v9
	v_add_f32_e32 v7, v11, v7
	v_and_b32_e32 v11, 0xffff0000, v143
	v_lshlrev_b32_e32 v9, 16, v143
	v_mul_f32_e32 v11, v11, v11
	v_fmac_f32_e32 v11, v9, v9
	v_add_f32_e32 v7, v11, v7
	v_and_b32_e32 v11, 0xffff0000, v144
	v_lshlrev_b32_e32 v9, 16, v144
	v_mul_f32_e32 v11, v11, v11
	v_fmac_f32_e32 v11, v9, v9
	v_add_f32_e32 v7, v11, v7
	v_and_b32_e32 v11, 0xffff0000, v145
	v_lshlrev_b32_e32 v9, 16, v145
	v_mul_f32_e32 v11, v11, v11
	v_fmac_f32_e32 v11, v9, v9
	v_add_f32_e32 v17, v11, v7
	v_xor_b32_e32 v7, 32, v253
	v_cmp_lt_i32_e32 vcc, v7, v226
	v_mov_b32_e32 v9, v4
	v_mov_b32_e32 v11, v4
	v_cndmask_b32_e32 v7, v253, v7, vcc
	v_lshlrev_b32_e32 v181, 2, v7
	ds_bpermute_b32 v18, v181, v17
	v_mov_b32_e32 v7, v4
	s_cmp_lt_u32 s4, 33
	v_mov_b32_e32 v13, v4
	s_cbranch_scc1 .LBB0_1300
	s_add_u32 s0, s0, 0x4000
	s_addc_u32 s1, s1, 0
	v_lshl_add_u64 v[26:27], s[0:1], 0, v[6:7]
	v_lshl_add_u64 v[20:21], s[2:3], 0, v[10:11]
	v_lshl_add_u64 v[22:23], s[2:3], 0, v[12:13]
	v_lshl_add_u64 v[24:25], s[0:1], 0, v[8:9]
; #define GAS __attribute__((address_space(1)))
; __device__ __forceinline__ void dsa_unit32(const Args& a, LAS unsigned char* lds, const LAS unsigned long long* maskl, int b, int qb, int tid, int wave, int lane) {
;     ...
;     const float negB = -1.01f * 11.313708498984761f * sqrtf(qs);
;     const int nkt = (t0 + 32 + 63) >> 6;
;     f32x16 O[4];
; #pragma unroll
;     for (int ct = 0; ct < 4; ++ct)
; #pragma unroll
;         for (int i = 0; i < 16; ++i) O[ct][i] = 0.f;
;     float l = 0.f;
;     u32x4 rk0[2], rv0[2], rk1[2], rv1[2];
;     const unsigned vok0 = (unsigned)((tid >> 4) * 128 + 8 * (tid & 15)) * 2u, vok1 = vok0 + 32u * 128u * 2u;
;     const unsigned vov0 = (unsigned)((tid >> 3) * SEQ + 8 * (tid & 7)) * 2u, vov1 = vov0 + 64u * (unsigned)SEQ * 2u;
;     const GAS char* ckb = (const GAS char*)ckv + (size_t)rowb * 256; const GAS char* cvb = (const GAS char*)ckvT + (size_t)b * 128 * SEQ * 2;
.LBB0_1300:
	s_waitcnt lgkmcnt(0)
	v_add_f32_e32 v17, v17, v18
	s_mov_b32 s0, 0xf800000
	v_mul_f32_e32 v18, 0x4f800000, v17
	v_cmp_gt_f32_e32 vcc, s0, v17
	v_add_u32_e32 v195, 0, v16
	v_lshrrev_b32_e32 v16, 4, v15
	v_cndmask_b32_e32 v17, v17, v18, vcc
	v_sqrt_f32_e32 v18, v17
	s_movk_i32 s0, 0x110
	v_mul_lo_u32 v16, v16, s0
	s_movk_i32 s1, 0x98
	v_add_u32_e32 v20, -1, v18
	v_fma_f32 v21, -v20, v18, v17
	v_cmp_ge_f32_e64 s[6:7], 0, v21
	v_add_u32_e32 v21, 1, v18
	v_mad_u32_u24 v202, v5, s0, 0
	v_cndmask_b32_e64 v20, v18, v20, s[6:7]
	v_fma_f32 v18, -v21, v18, v17
	v_cmp_lt_f32_e64 s[6:7], 0, v18
	v_lshlrev_b32_e32 v19, 3, v14
	v_lshlrev_b32_e32 v182, 2, v14
	v_cndmask_b32_e64 v18, v20, v21, s[6:7]
	v_mul_f32_e32 v20, 0x37800000, v18
	v_cndmask_b32_e32 v18, v18, v20, vcc
	v_cmp_class_f32_e32 vcc, v17, v185
	v_mov_b32_e32 v194, 0
	s_addk_i32 s4, 0x5f
	v_cndmask_b32_e32 v17, v18, v17, vcc
	v_mul_f32_e32 v70, 0xc136d45c, v17
	v_and_b32_e32 v17, 0xf0, v6
	v_add_u32_e32 v17, 0, v17
	v_add_u32_e32 v196, v17, v16
	v_lshrrev_b32_e32 v16, 3, v15
	v_add_u32_e32 v15, 0x200, v15
	v_mul_lo_u32 v197, v16, s1
	v_lshrrev_b32_e32 v16, 4, v15
	v_mul_lo_u32 v16, v16, s0
	v_lshrrev_b32_e32 v15, 3, v15
	s_movk_i32 s0, 0xff88
	v_mul_lo_u32 v200, v15, s1
	v_mad_i32_i24 v14, v5, s0, v202
	v_readlane_b32 s0, v254, 28
	v_readlane_b32 s1, v254, 29
	s_movk_i32 s2, 0x4400
	v_add_u32_e32 v203, v14, v19
	v_add_u32_e32 v14, 0xd400, v14
	v_lshl_add_u64 v[186:187], s[0:1], 0, v[12:13]
	v_lshl_add_u64 v[188:189], s[0:1], 0, v[10:11]
	v_readlane_b32 s0, v254, 40
	v_mov_b32_e32 v179, v4
	s_lshr_b32 s4, s4, 6
	s_mov_b32 s5, 3
	v_add3_u32 v198, v195, v197, s2
	v_add_u32_e32 v199, v17, v16
	v_add3_u32 v201, v195, v200, s2
	v_mov_b32_e32 v71, v70
	v_mov_b32_e32 v72, v70
	v_mov_b32_e32 v73, v70
	v_mov_b32_e32 v74, v70
	v_mov_b32_e32 v75, v70
	v_mov_b32_e32 v76, v70
	v_mov_b32_e32 v77, v70
	v_mov_b32_e32 v78, v70
	v_mov_b32_e32 v79, v70
	v_mov_b32_e32 v80, v70
	v_mov_b32_e32 v81, v70
	v_mov_b32_e32 v82, v70
	v_mov_b32_e32 v83, v70
	v_mov_b32_e32 v84, v70
	v_mov_b32_e32 v85, v70
	v_or_b32_e32 v184, 32, v182
	v_add_u32_e32 v204, 0xd400, v203
	v_lshl_add_u64 v[190:191], s[8:9], 0, v[8:9]
	v_lshl_add_u64 v[192:193], s[8:9], 0, v[6:7]
	v_lshl_add_u32 v206, v5, 8, s0
	v_mov_b32_e32 v54, 0
	v_mov_b32_e32 v55, v194
	v_mov_b32_e32 v56, v194
	v_mov_b32_e32 v57, v194
	v_mov_b32_e32 v58, v194
	v_mov_b32_e32 v59, v194
	v_mov_b32_e32 v60, v194
	v_mov_b32_e32 v61, v194
	v_mov_b32_e32 v62, v194
	v_mov_b32_e32 v63, v194
	v_mov_b32_e32 v64, v194
	v_mov_b32_e32 v65, v194
	v_mov_b32_e32 v66, v194
	v_mov_b32_e32 v67, v194
	v_mov_b32_e32 v68, v194
	v_mov_b32_e32 v69, v194
	v_mov_b32_e32 v38, 0
	v_mov_b32_e32 v39, v194
	v_mov_b32_e32 v40, v194
	v_mov_b32_e32 v41, v194
	v_mov_b32_e32 v42, v194
	v_mov_b32_e32 v43, v194
	v_mov_b32_e32 v44, v194
	v_mov_b32_e32 v45, v194
	v_mov_b32_e32 v46, v194
	v_mov_b32_e32 v47, v194
	v_mov_b32_e32 v48, v194
	v_mov_b32_e32 v49, v194
	v_mov_b32_e32 v50, v194
	v_mov_b32_e32 v51, v194
	v_mov_b32_e32 v52, v194
	v_mov_b32_e32 v53, v194
	v_mov_b32_e32 v22, 0
	v_mov_b32_e32 v23, v194
	v_mov_b32_e32 v24, v194
	v_mov_b32_e32 v25, v194
	v_mov_b32_e32 v26, v194
	v_mov_b32_e32 v27, v194
	v_mov_b32_e32 v28, v194
	v_mov_b32_e32 v29, v194
	v_mov_b32_e32 v30, v194
	v_mov_b32_e32 v31, v194
	v_mov_b32_e32 v32, v194
	v_mov_b32_e32 v33, v194
	v_mov_b32_e32 v34, v194
	v_mov_b32_e32 v35, v194
	v_mov_b32_e32 v36, v194
	v_mov_b32_e32 v37, v194
	v_mov_b32_e32 v6, 0
	v_mov_b32_e32 v7, v194
	v_mov_b32_e32 v8, v194
	v_mov_b32_e32 v9, v194
	v_mov_b32_e32 v10, v194
	v_mov_b32_e32 v11, v194
	v_mov_b32_e32 v12, v194
	v_mov_b32_e32 v13, v194
	v_mov_b32_e32 v14, v194
	v_mov_b32_e32 v15, v194
	v_mov_b32_e32 v16, v194
	v_mov_b32_e32 v17, v194
	v_mov_b32_e32 v18, v194
	v_mov_b32_e32 v19, v194
	v_mov_b32_e32 v20, v194
	v_mov_b32_e32 v21, v194
	ds_write_b128 v196, v[146:149]
	ds_write2_b64 v198, v[154:155], v[156:157] offset1:1
	ds_write_b128 v199, v[150:153]
	ds_write2_b64 v201, v[158:159], v[160:161] offset1:1
	s_waitcnt lgkmcnt(0)
	s_barrier
	s_branch .LBB0_1302
